# scan pass C: per-chunk q/gate loads no longer drained at the loop top (vmcnt(0) -> counted), group-norm gains loaded once per item
# speedup vs baseline: 1.0303x; 1.0029x over previous
.LBB0_140:
	s_nop 0
	v_add_u32_e32 v18, s51, v115
	v_lshl_or_b32 v192, v18, 14, v173
	v_or_b32_e32 v2, 0x80, v192
	v_mov_b32_e32 v3, v193
	v_lshl_add_u64 v[0:1], v[192:193], 2, s[60:61]
	v_lshl_add_u64 v[2:3], v[2:3], 2, s[60:61]
	global_load_dword v0, v[0:1], off
	v_or_b32_e32 v4, 0x180, v192
	global_load_dword v1, v[2:3], off
	v_or_b32_e32 v2, 0x100, v192
	v_mov_b32_e32 v3, v193
	v_mov_b32_e32 v5, v193
	v_lshl_add_u64 v[2:3], v[2:3], 2, s[60:61]
	v_lshl_add_u64 v[4:5], v[4:5], 2, s[60:61]
	global_load_dword v2, v[2:3], off
	v_or_b32_e32 v6, 0x480, v192
	global_load_dword v3, v[4:5], off
	v_or_b32_e32 v4, 0x400, v192
	v_mov_b32_e32 v5, v193
	v_mov_b32_e32 v7, v193
	v_lshl_add_u64 v[4:5], v[4:5], 2, s[60:61]
	v_lshl_add_u64 v[6:7], v[6:7], 2, s[60:61]
	global_load_dword v4, v[4:5], off
	v_or_b32_e32 v8, 0x580, v192
	global_load_dword v5, v[6:7], off
	v_or_b32_e32 v6, 0x500, v192
	v_mov_b32_e32 v7, v193
	v_mov_b32_e32 v9, v193
	v_lshl_add_u64 v[6:7], v[6:7], 2, s[60:61]
	v_lshl_add_u64 v[8:9], v[8:9], 2, s[60:61]
	global_load_dword v6, v[6:7], off
	v_or_b32_e32 v10, 0x880, v192
	global_load_dword v7, v[8:9], off
	v_or_b32_e32 v8, 0x800, v192
	v_mov_b32_e32 v9, v193
	v_mov_b32_e32 v11, v193
	v_lshl_add_u64 v[8:9], v[8:9], 2, s[60:61]
	v_lshl_add_u64 v[10:11], v[10:11], 2, s[60:61]
	global_load_dword v8, v[8:9], off
	v_or_b32_e32 v12, 0x980, v192
	global_load_dword v9, v[10:11], off
	v_or_b32_e32 v10, 0x900, v192
	v_mov_b32_e32 v11, v193
	v_mov_b32_e32 v13, v193
	v_lshl_add_u64 v[10:11], v[10:11], 2, s[60:61]
	v_lshl_add_u64 v[12:13], v[12:13], 2, s[60:61]
	global_load_dword v10, v[10:11], off
	v_or_b32_e32 v14, 0xc80, v192
	global_load_dword v11, v[12:13], off
	v_or_b32_e32 v12, 0xc00, v192
	v_mov_b32_e32 v13, v193
	v_mov_b32_e32 v15, v193
	v_lshl_add_u64 v[12:13], v[12:13], 2, s[60:61]
	v_lshl_add_u64 v[14:15], v[14:15], 2, s[60:61]
	global_load_dword v12, v[12:13], off
	v_or_b32_e32 v16, 0xd80, v192
	global_load_dword v13, v[14:15], off
	v_or_b32_e32 v14, 0xd00, v192
	v_mov_b32_e32 v15, v193
	v_mov_b32_e32 v17, v193
	v_lshl_add_u64 v[14:15], v[14:15], 2, s[60:61]
	v_lshl_add_u64 v[16:17], v[16:17], 2, s[60:61]
	global_load_dword v14, v[14:15], off
	s_nop 0
	global_load_dword v15, v[16:17], off
	v_ashrrev_i32_e32 v16, 31, v18
	v_lshrrev_b32_e32 v16, 28, v16
	v_add_u32_e32 v16, v18, v16
	v_ashrrev_i32_e32 v155, 4, v16
	v_ashrrev_i32_e32 v64, 7, v16
	v_and_b32_e32 v16, -16, v16
	v_sub_u32_e32 v158, v18, v16
	v_or_b32_e32 v16, 0x1000, v192
	v_mov_b32_e32 v17, v193
	v_or_b32_e32 v18, 0x1080, v192
	v_mov_b32_e32 v19, v193
	v_lshl_add_u64 v[16:17], v[16:17], 2, s[60:61]
	v_lshl_add_u64 v[18:19], v[18:19], 2, s[60:61]
	global_load_dword v16, v[16:17], off
	v_or_b32_e32 v20, 0x1180, v192
	global_load_dword v17, v[18:19], off
	v_or_b32_e32 v18, 0x1100, v192
	v_mov_b32_e32 v19, v193
	v_mov_b32_e32 v21, v193
	v_lshl_add_u64 v[18:19], v[18:19], 2, s[60:61]
	v_lshl_add_u64 v[20:21], v[20:21], 2, s[60:61]
	global_load_dword v18, v[18:19], off
	v_or_b32_e32 v22, 0x1480, v192
	global_load_dword v19, v[20:21], off
	v_or_b32_e32 v20, 0x1400, v192
	v_mov_b32_e32 v21, v193
	v_mov_b32_e32 v23, v193
	v_lshl_add_u64 v[20:21], v[20:21], 2, s[60:61]
	v_lshl_add_u64 v[22:23], v[22:23], 2, s[60:61]
	global_load_dword v20, v[20:21], off
	v_or_b32_e32 v24, 0x1580, v192
	global_load_dword v21, v[22:23], off
	v_or_b32_e32 v22, 0x1500, v192
	v_mov_b32_e32 v23, v193
	v_mov_b32_e32 v25, v193
	v_lshl_add_u64 v[22:23], v[22:23], 2, s[60:61]
	v_lshl_add_u64 v[24:25], v[24:25], 2, s[60:61]
	global_load_dword v22, v[22:23], off
	v_or_b32_e32 v26, 0x1880, v192
	global_load_dword v23, v[24:25], off
	v_or_b32_e32 v24, 0x1800, v192
	v_mov_b32_e32 v25, v193
	v_mov_b32_e32 v27, v193
	v_lshl_add_u64 v[24:25], v[24:25], 2, s[60:61]
	v_lshl_add_u64 v[26:27], v[26:27], 2, s[60:61]
	global_load_dword v24, v[24:25], off
	v_or_b32_e32 v28, 0x1980, v192
	global_load_dword v25, v[26:27], off
	v_or_b32_e32 v26, 0x1900, v192
	v_mov_b32_e32 v27, v193
	v_mov_b32_e32 v29, v193
	v_lshl_add_u64 v[26:27], v[26:27], 2, s[60:61]
	v_lshl_add_u64 v[28:29], v[28:29], 2, s[60:61]
	global_load_dword v26, v[26:27], off
	v_or_b32_e32 v30, 0x1c80, v192
	global_load_dword v27, v[28:29], off
	v_or_b32_e32 v28, 0x1c00, v192
	v_mov_b32_e32 v29, v193
	v_mov_b32_e32 v31, v193
	v_lshl_add_u64 v[28:29], v[28:29], 2, s[60:61]
	v_lshl_add_u64 v[30:31], v[30:31], 2, s[60:61]
	global_load_dword v28, v[28:29], off
	v_or_b32_e32 v32, 0x1d80, v192
	global_load_dword v29, v[30:31], off
	v_or_b32_e32 v30, 0x1d00, v192
	v_mov_b32_e32 v31, v193
	v_mov_b32_e32 v33, v193
	v_lshl_add_u64 v[30:31], v[30:31], 2, s[60:61]
	v_lshl_add_u64 v[32:33], v[32:33], 2, s[60:61]
	global_load_dword v30, v[30:31], off
	s_nop 0
	global_load_dword v31, v[32:33], off
	v_or_b32_e32 v32, 0x2000, v192
	v_mov_b32_e32 v33, v193
	v_or_b32_e32 v34, 0x2080, v192
	v_mov_b32_e32 v35, v193
	v_lshl_add_u64 v[32:33], v[32:33], 2, s[60:61]
	v_lshl_add_u64 v[34:35], v[34:35], 2, s[60:61]
	global_load_dword v32, v[32:33], off
	v_or_b32_e32 v36, 0x2180, v192
	global_load_dword v33, v[34:35], off
	v_or_b32_e32 v34, 0x2100, v192
	v_mov_b32_e32 v35, v193
	v_mov_b32_e32 v37, v193
	v_lshl_add_u64 v[34:35], v[34:35], 2, s[60:61]
	v_lshl_add_u64 v[36:37], v[36:37], 2, s[60:61]
	global_load_dword v34, v[34:35], off
	v_or_b32_e32 v38, 0x2480, v192
	global_load_dword v35, v[36:37], off
	v_or_b32_e32 v36, 0x2400, v192
	v_mov_b32_e32 v37, v193
	v_mov_b32_e32 v39, v193
	v_lshl_add_u64 v[36:37], v[36:37], 2, s[60:61]
	v_lshl_add_u64 v[38:39], v[38:39], 2, s[60:61]
	global_load_dword v36, v[36:37], off
	v_or_b32_e32 v40, 0x2580, v192
	global_load_dword v37, v[38:39], off
	v_or_b32_e32 v38, 0x2500, v192
	v_mov_b32_e32 v39, v193
	v_mov_b32_e32 v41, v193
	v_lshl_add_u64 v[38:39], v[38:39], 2, s[60:61]
	v_lshl_add_u64 v[40:41], v[40:41], 2, s[60:61]
	global_load_dword v38, v[38:39], off
	v_or_b32_e32 v42, 0x2880, v192
	global_load_dword v39, v[40:41], off
	v_or_b32_e32 v40, 0x2800, v192
	v_mov_b32_e32 v41, v193
	v_mov_b32_e32 v43, v193
	v_lshl_add_u64 v[40:41], v[40:41], 2, s[60:61]
	v_lshl_add_u64 v[42:43], v[42:43], 2, s[60:61]
	global_load_dword v40, v[40:41], off
	v_or_b32_e32 v44, 0x2980, v192
	global_load_dword v41, v[42:43], off
	v_or_b32_e32 v42, 0x2900, v192
	v_mov_b32_e32 v43, v193
	v_mov_b32_e32 v45, v193
	v_lshl_add_u64 v[42:43], v[42:43], 2, s[60:61]
	v_lshl_add_u64 v[44:45], v[44:45], 2, s[60:61]
	global_load_dword v42, v[42:43], off
	v_or_b32_e32 v46, 0x2c80, v192
	global_load_dword v43, v[44:45], off
	v_or_b32_e32 v44, 0x2c00, v192
	v_mov_b32_e32 v45, v193
	v_mov_b32_e32 v47, v193
	v_lshl_add_u64 v[44:45], v[44:45], 2, s[60:61]
	v_lshl_add_u64 v[46:47], v[46:47], 2, s[60:61]
	global_load_dword v44, v[44:45], off
	v_or_b32_e32 v48, 0x2d80, v192
	global_load_dword v45, v[46:47], off
	v_or_b32_e32 v46, 0x2d00, v192
	v_mov_b32_e32 v47, v193
	v_mov_b32_e32 v49, v193
	v_lshl_add_u64 v[46:47], v[46:47], 2, s[60:61]
	v_lshl_add_u64 v[48:49], v[48:49], 2, s[60:61]
	global_load_dword v46, v[46:47], off
	s_nop 0
	global_load_dword v47, v[48:49], off
	v_or_b32_e32 v48, 0x3000, v192
	v_mov_b32_e32 v49, v193
	v_or_b32_e32 v50, 0x3080, v192
	v_mov_b32_e32 v51, v193
	v_lshl_add_u64 v[48:49], v[48:49], 2, s[60:61]
	v_lshl_add_u64 v[50:51], v[50:51], 2, s[60:61]
	global_load_dword v48, v[48:49], off
	v_or_b32_e32 v52, 0x3180, v192
	global_load_dword v49, v[50:51], off
	v_or_b32_e32 v50, 0x3100, v192
	v_mov_b32_e32 v51, v193
	v_mov_b32_e32 v53, v193
	v_lshl_add_u64 v[50:51], v[50:51], 2, s[60:61]
	v_lshl_add_u64 v[52:53], v[52:53], 2, s[60:61]
	global_load_dword v50, v[50:51], off
	v_or_b32_e32 v54, 0x3480, v192
	global_load_dword v51, v[52:53], off
	v_or_b32_e32 v52, 0x3400, v192
	v_mov_b32_e32 v53, v193
	v_mov_b32_e32 v55, v193
	v_lshl_add_u64 v[52:53], v[52:53], 2, s[60:61]
	v_lshl_add_u64 v[54:55], v[54:55], 2, s[60:61]
	global_load_dword v52, v[52:53], off
	v_or_b32_e32 v56, 0x3580, v192
	global_load_dword v53, v[54:55], off
	v_or_b32_e32 v54, 0x3500, v192
	v_mov_b32_e32 v55, v193
	v_mov_b32_e32 v57, v193
	v_lshl_add_u64 v[54:55], v[54:55], 2, s[60:61]
	v_lshl_add_u64 v[56:57], v[56:57], 2, s[60:61]
	global_load_dword v54, v[54:55], off
	v_or_b32_e32 v58, 0x3880, v192
	global_load_dword v55, v[56:57], off
	v_or_b32_e32 v56, 0x3800, v192
	v_mov_b32_e32 v57, v193
	v_mov_b32_e32 v59, v193
	v_lshl_add_u64 v[56:57], v[56:57], 2, s[60:61]
	v_lshl_add_u64 v[58:59], v[58:59], 2, s[60:61]
	global_load_dword v56, v[56:57], off
	v_or_b32_e32 v60, 0x3980, v192
	global_load_dword v57, v[58:59], off
	v_or_b32_e32 v58, 0x3900, v192
	v_mov_b32_e32 v59, v193
	v_mov_b32_e32 v61, v193
	v_lshl_add_u64 v[58:59], v[58:59], 2, s[60:61]
	v_lshl_add_u64 v[60:61], v[60:61], 2, s[60:61]
	global_load_dword v58, v[58:59], off
	v_or_b32_e32 v62, 0x3c80, v192
	global_load_dword v59, v[60:61], off
	v_or_b32_e32 v60, 0x3c00, v192
	v_mov_b32_e32 v61, v193
	v_mov_b32_e32 v63, v193
	v_lshl_add_u64 v[60:61], v[60:61], 2, s[60:61]
	v_lshl_add_u64 v[62:63], v[62:63], 2, s[60:61]
	global_load_dword v60, v[60:61], off
	s_nop 0
	global_load_dword v61, v[62:63], off
	v_or_b32_e32 v62, 0x3d00, v192
	v_mov_b32_e32 v63, v193
	v_or_b32_e32 v192, 0x3d80, v192
	v_lshl_add_u64 v[62:63], v[62:63], 2, s[60:61]
	v_lshl_add_u64 v[66:67], v[192:193], 2, s[60:61]
	global_load_dword v62, v[62:63], off
	s_nop 0
	global_load_dword v63, v[66:67], off
	v_ashrrev_i32_e32 v65, 31, v64
	v_ashrrev_i32_e32 v159, 31, v158
	v_and_b32_e32 v157, 7, v155
	v_lshlrev_b64 v[64:65], 12, v[64:65]
	v_lshlrev_b64 v[66:67], 8, v[158:159]
	v_lshl_add_u64 v[64:65], v[64:65], 0, v[66:67]
	v_or_b32_e32 v160, v64, v118
	v_mov_b32_e32 v161, v65
	v_lshlrev_b64 v[66:67], 10, v[160:161]
	v_lshlrev_b32_e32 v72, 7, v157
	v_or_b32_e32 v66, v66, v114
	v_or_b32_e32 v66, v66, v72
	v_lshl_add_u64 v[68:69], v[66:67], 2, s[92:93]
	global_load_dword v112, v[68:69], off
	v_lshl_add_u64 v[68:69], v[66:67], 1, s[84:85]
	global_load_ushort v105, v[68:69], off
	v_or_b32_e32 v68, 0x400, v66
	v_mov_b32_e32 v69, v67
	v_lshl_add_u64 v[70:71], v[68:69], 2, s[92:93]
	v_lshl_add_u64 v[68:69], v[68:69], 1, s[84:85]
	global_load_dword v181, v[70:71], off
	global_load_ushort v106, v[68:69], off
	v_or_b32_e32 v68, 0x800, v66
	v_mov_b32_e32 v69, v67
	v_lshl_add_u64 v[70:71], v[68:69], 2, s[92:93]
	v_lshl_add_u64 v[68:69], v[68:69], 1, s[84:85]
	global_load_dword v182, v[70:71], off
	global_load_ushort v107, v[68:69], off
	v_or_b32_e32 v68, 0xc00, v66
	v_mov_b32_e32 v69, v67
	v_lshl_add_u64 v[70:71], v[68:69], 2, s[92:93]
	v_lshl_add_u64 v[68:69], v[68:69], 1, s[84:85]
	global_load_dword v184, v[70:71], off
	global_load_ushort v108, v[68:69], off
	v_or_b32_e32 v68, 0x1000, v66
	v_mov_b32_e32 v69, v67
	v_lshl_add_u64 v[70:71], v[68:69], 2, s[92:93]
	v_lshl_add_u64 v[68:69], v[68:69], 1, s[84:85]
	global_load_dword v186, v[70:71], off
	global_load_ushort v109, v[68:69], off
	v_or_b32_e32 v68, 0x1400, v66
	v_mov_b32_e32 v69, v67
	v_lshl_add_u64 v[70:71], v[68:69], 2, s[92:93]
	v_lshl_add_u64 v[68:69], v[68:69], 1, s[84:85]
	global_load_dword v188, v[70:71], off
	global_load_ushort v110, v[68:69], off
	v_or_b32_e32 v68, 0x1800, v66
	v_mov_b32_e32 v69, v67
	v_lshl_add_u64 v[70:71], v[68:69], 2, s[92:93]
	v_lshl_add_u64 v[68:69], v[68:69], 1, s[84:85]
	global_load_dword v190, v[70:71], off
	global_load_ushort v111, v[68:69], off
	v_or_b32_e32 v68, 0x1c00, v66
	v_mov_b32_e32 v69, v67
	v_lshl_add_u64 v[70:71], v[68:69], 2, s[92:93]
	v_lshl_add_u64 v[68:69], v[68:69], 1, s[84:85]
	global_load_dword v192, v[70:71], off
	global_load_ushort v113, v[68:69], off
	v_or_b32_e32 v68, 0x2000, v66
	v_mov_b32_e32 v69, v67
	v_lshl_add_u64 v[70:71], v[68:69], 2, s[92:93]
	v_lshl_add_u64 v[68:69], v[68:69], 1, s[84:85]
	global_load_dword v195, v[70:71], off
	global_load_ushort v159, v[68:69], off
	v_or_b32_e32 v68, 0x2400, v66
	v_mov_b32_e32 v69, v67
	v_lshl_add_u64 v[70:71], v[68:69], 2, s[92:93]
	v_lshl_add_u64 v[68:69], v[68:69], 1, s[84:85]
	global_load_dword v196, v[70:71], off
	global_load_ushort v183, v[68:69], off
	v_or_b32_e32 v68, 0x2800, v66
	v_mov_b32_e32 v69, v67
	v_lshl_add_u64 v[70:71], v[68:69], 2, s[92:93]
	v_lshl_add_u64 v[68:69], v[68:69], 1, s[84:85]
	global_load_dword v198, v[70:71], off
	global_load_ushort v185, v[68:69], off
	v_or_b32_e32 v68, 0x2c00, v66
	v_mov_b32_e32 v69, v67
	v_lshl_add_u64 v[70:71], v[68:69], 2, s[92:93]
	v_lshl_add_u64 v[68:69], v[68:69], 1, s[84:85]
	global_load_dword v200, v[70:71], off
	global_load_ushort v187, v[68:69], off
	v_or_b32_e32 v68, 0x3000, v66
	v_mov_b32_e32 v69, v67
	v_lshl_add_u64 v[70:71], v[68:69], 2, s[92:93]
	v_lshl_add_u64 v[68:69], v[68:69], 1, s[84:85]
	global_load_dword v201, v[70:71], off
	global_load_ushort v189, v[68:69], off
	v_or_b32_e32 v68, 0x3400, v66
	v_mov_b32_e32 v69, v67
	v_lshl_add_u64 v[70:71], v[68:69], 2, s[92:93]
	v_lshl_add_u64 v[68:69], v[68:69], 1, s[84:85]
	global_load_dword v202, v[70:71], off
	global_load_ushort v191, v[68:69], off
	v_or_b32_e32 v68, 0x3800, v66
	v_mov_b32_e32 v69, v67
	v_lshl_add_u64 v[70:71], v[68:69], 2, s[92:93]
	v_lshl_add_u64 v[68:69], v[68:69], 1, s[84:85]
	v_or_b32_e32 v66, 0x3c00, v66
	global_load_dword v203, v[70:71], off
	global_load_ushort v194, v[68:69], off
	v_lshl_add_u64 v[68:69], v[66:67], 2, s[92:93]
	v_lshl_add_u64 v[66:67], v[66:67], 1, s[84:85]
	global_load_dword v199, v[68:69], off
	global_load_ushort v197, v[66:67], off
	v_or_b32_e32 v64, v64, v116
	v_lshlrev_b64 v[64:65], 10, v[64:65]
	v_or_b32_e32 v64, v120, v64
	v_or_b32_e32 v64, v64, v72
	v_or_b32_e32 v162, v114, v72
	v_lshl_add_u64 v[164:165], v[64:65], 1, s[56:57]
	s_mov_b64 s[44:45], 0
	s_mov_b32 s52, 32
	s_load_dwordx2 s[48:49], s[0:1], 0x70
	s_lshl_b64 s[54:55], s[2:3], 2
	v_and_b32_e32 v212, 7, v220
	v_lshlrev_b32_e32 v212, 6, v212
	s_waitcnt lgkmcnt(0)
	s_add_u32 s48, s48, s54
	s_addc_u32 s49, s49, s55
	global_load_dwordx4 v[216:219], v212, s[48:49] offset:16
	global_load_dwordx4 v[244:247], v212, s[48:49] offset:32
	global_load_dwordx4 v[248:251], v212, s[48:49] offset:48
	global_load_dwordx4 v[212:215], v212, s[48:49]
	s_branch .LBB0_142
.LBB0_141:
	s_or_b64 exec, exec, s[48:49]
	s_waitcnt lgkmcnt(1)
	v_sub_f32_e32 v92, v106, v110
	v_sub_f32_e32 v93, v107, v111
	v_exp_f32_e32 v110, v106
	v_exp_f32_e32 v111, v107
	v_max_f32_e64 v106, -v106, -v106
	v_max_f32_e64 v107, -v107, -v107
	v_exp_f32_e32 v92, v92
	v_exp_f32_e32 v93, v93
	v_min_f32_e32 v106, 0x42e60000, v106
	v_min_f32_e32 v107, 0x42e60000, v107
	v_exp_f32_e32 v106, v106
	v_exp_f32_e32 v107, v107
	v_pk_add_f32 v[92:93], v[92:93], 1.0 op_sel_hi:[1,0] neg_lo:[1,0] neg_hi:[1,0]
	s_waitcnt vmcnt(2)
	v_lshlrev_b32_e32 v182, 16, v64
	v_and_b32_e32 v183, 0xffff0000, v64
	v_pk_mul_f32 v[92:93], v[106:107], v[92:93]
	v_pk_mul_f32 v[110:111], v[110:111], v[182:183]
	v_cvt_pk_bf16_f32 v92, v92, v93
	v_sub_f32_e32 v93, v108, v112
	v_exp_f32_e32 v106, v93
	v_sub_f32_e32 v93, v109, v113
	v_exp_f32_e32 v107, v93
	v_max_f32_e64 v93, -v108, -v108
	v_min_f32_e32 v93, 0x42e60000, v93
	v_cvt_pk_bf16_f32 v64, v110, v111
	v_exp_f32_e32 v110, v108
	v_exp_f32_e32 v108, v93
	v_max_f32_e64 v93, -v109, -v109
	v_min_f32_e32 v93, 0x42e60000, v93
	v_exp_f32_e32 v111, v109
	v_exp_f32_e32 v109, v93
	v_pk_add_f32 v[106:107], v[106:107], 1.0 op_sel_hi:[1,0] neg_lo:[1,0] neg_hi:[1,0]
	v_sub_f32_e32 v98, v102, v98
	v_sub_f32_e32 v99, v103, v99
	v_pk_mul_f32 v[106:107], v[108:109], v[106:107]
	v_exp_f32_e32 v98, v98
	v_cvt_pk_bf16_f32 v93, v106, v107
	v_exp_f32_e32 v106, v102
	v_exp_f32_e32 v107, v103
	v_max_f32_e64 v102, -v102, -v102
	v_max_f32_e64 v103, -v103, -v103
	v_exp_f32_e32 v99, v99
	v_min_f32_e32 v102, 0x42e60000, v102
	v_min_f32_e32 v103, 0x42e60000, v103
	v_exp_f32_e32 v102, v102
	v_exp_f32_e32 v103, v103
	v_pk_add_f32 v[98:99], v[98:99], 1.0 op_sel_hi:[1,0] neg_lo:[1,0] neg_hi:[1,0]
	v_lshlrev_b32_e32 v108, 16, v70
	v_and_b32_e32 v109, 0xffff0000, v70
	v_pk_mul_f32 v[98:99], v[102:103], v[98:99]
	v_pk_mul_f32 v[106:107], v[106:107], v[108:109]
	v_cvt_pk_bf16_f32 v102, v98, v99
	v_sub_f32_e32 v98, v104, v100
	v_sub_f32_e32 v99, v105, v101
	v_exp_f32_e32 v100, v104
	v_exp_f32_e32 v101, v105
	v_cvt_pk_bf16_f32 v70, v106, v107
	v_lshlrev_b32_e32 v106, 16, v71
	v_and_b32_e32 v107, 0xffff0000, v71
	v_pk_mul_f32 v[100:101], v[100:101], v[106:107]
	v_exp_f32_e32 v98, v98
	v_cvt_pk_bf16_f32 v71, v100, v101
	v_max_f32_e64 v100, -v104, -v104
	v_max_f32_e64 v101, -v105, -v105
	v_exp_f32_e32 v99, v99
	v_min_f32_e32 v100, 0x42e60000, v100
	v_min_f32_e32 v101, 0x42e60000, v101
	v_exp_f32_e32 v100, v100
	v_exp_f32_e32 v101, v101
	v_pk_add_f32 v[98:99], v[98:99], 1.0 op_sel_hi:[1,0] neg_lo:[1,0] neg_hi:[1,0]
	v_sub_f32_e32 v94, v88, v94
	v_sub_f32_e32 v95, v89, v95
	v_pk_mul_f32 v[98:99], v[100:101], v[98:99]
	v_exp_f32_e32 v94, v94
	v_cvt_pk_bf16_f32 v103, v98, v99
	v_exp_f32_e32 v98, v88
	v_exp_f32_e32 v99, v89
	v_max_f32_e64 v88, -v88, -v88
	v_max_f32_e64 v89, -v89, -v89
	v_exp_f32_e32 v95, v95
	v_min_f32_e32 v88, 0x42e60000, v88
	v_min_f32_e32 v89, 0x42e60000, v89
	v_exp_f32_e32 v88, v88
	v_exp_f32_e32 v89, v89
	v_pk_add_f32 v[94:95], v[94:95], 1.0 op_sel_hi:[1,0] neg_lo:[1,0] neg_hi:[1,0]
	v_lshlrev_b32_e32 v100, 16, v68
	v_and_b32_e32 v101, 0xffff0000, v68
	v_pk_mul_f32 v[88:89], v[88:89], v[94:95]
	v_pk_mul_f32 v[98:99], v[98:99], v[100:101]
	v_cvt_pk_bf16_f32 v100, v88, v89
	v_sub_f32_e32 v88, v90, v96
	v_sub_f32_e32 v89, v91, v97
	v_exp_f32_e32 v94, v90
	v_exp_f32_e32 v95, v91
	v_max_f32_e64 v90, -v90, -v90
	v_max_f32_e64 v91, -v91, -v91
	v_exp_f32_e32 v88, v88
	v_exp_f32_e32 v89, v89
	v_min_f32_e32 v90, 0x42e60000, v90
	v_min_f32_e32 v91, 0x42e60000, v91
	v_exp_f32_e32 v90, v90
	v_exp_f32_e32 v91, v91
	v_pk_add_f32 v[88:89], v[88:89], 1.0 op_sel_hi:[1,0] neg_lo:[1,0] neg_hi:[1,0]
	s_waitcnt lgkmcnt(0)
	v_sub_f32_e32 v72, v76, v72
	v_sub_f32_e32 v73, v77, v73
	v_pk_mul_f32 v[88:89], v[90:91], v[88:89]
	v_exp_f32_e32 v72, v72
	v_cvt_pk_bf16_f32 v101, v88, v89
	v_exp_f32_e32 v88, v76
	v_exp_f32_e32 v89, v77
	v_max_f32_e64 v76, -v76, -v76
	v_max_f32_e64 v77, -v77, -v77
	v_exp_f32_e32 v73, v73
	v_min_f32_e32 v76, 0x42e60000, v76
	v_min_f32_e32 v77, 0x42e60000, v77
	v_exp_f32_e32 v76, v76
	v_exp_f32_e32 v77, v77
	v_lshlrev_b32_e32 v96, 16, v69
	v_and_b32_e32 v97, 0xffff0000, v69
	v_pk_add_f32 v[72:73], v[72:73], 1.0 op_sel_hi:[1,0] neg_lo:[1,0] neg_hi:[1,0]
	v_pk_mul_f32 v[94:95], v[94:95], v[96:97]
	v_pk_mul_f32 v[72:73], v[76:77], v[72:73]
	v_cvt_pk_bf16_f32 v69, v94, v95
	v_cvt_pk_bf16_f32 v94, v72, v73
	v_sub_f32_e32 v72, v78, v74
	v_sub_f32_e32 v73, v79, v75
	v_exp_f32_e32 v74, v78
	v_exp_f32_e32 v75, v79
	v_lshlrev_b32_e32 v76, 16, v67
	v_and_b32_e32 v77, 0xffff0000, v67
	v_exp_f32_e32 v72, v72
	v_pk_mul_f32 v[74:75], v[74:75], v[76:77]
	v_exp_f32_e32 v73, v73
	v_cvt_pk_bf16_f32 v67, v74, v75
	v_max_f32_e64 v74, -v78, -v78
	v_max_f32_e64 v75, -v79, -v79
	v_min_f32_e32 v74, 0x42e60000, v74
	v_min_f32_e32 v75, 0x42e60000, v75
	v_exp_f32_e32 v74, v74
	v_exp_f32_e32 v75, v75
	v_lshlrev_b32_e32 v112, 16, v65
	v_and_b32_e32 v113, 0xffff0000, v65
	v_pk_mul_f32 v[110:111], v[110:111], v[112:113]
	v_lshlrev_b32_e32 v90, 16, v66
	v_and_b32_e32 v91, 0xffff0000, v66
	v_pk_add_f32 v[72:73], v[72:73], 1.0 op_sel_hi:[1,0] neg_lo:[1,0] neg_hi:[1,0]
	s_cmp_lg_u32 s44, 0x70000
	v_cvt_pk_bf16_f32 v65, v110, v111
	v_cvt_pk_bf16_f32 v68, v98, v99
	v_pk_mul_f32 v[88:89], v[88:89], v[90:91]
	v_pk_mul_f32 v[72:73], v[74:75], v[72:73]
	s_cselect_b32 s94, s52, 0xe0
	v_cvt_pk_bf16_f32 v66, v88, v89
	v_cvt_pk_bf16_f32 v95, v72, v73
	ds_write_b128 v169, v[68:71] offset:16896
	ds_write_b128 v169, v[64:67] offset:16912
	ds_write_b128 v169, v[100:103] offset:25600
	ds_write_b128 v169, v[92:95] offset:25616
	v_lshl_add_u64 v[64:65], v[160:161], 0, s[94:95]
	v_lshlrev_b64 v[64:65], 10, v[64:65]
	v_or_b32_e32 v64, v64, v162
	v_lshl_add_u64 v[66:67], v[64:65], 2, s[92:93]
	v_add_co_u32_e32 v68, vcc, s33, v66
	s_waitcnt lgkmcnt(0)
	s_barrier
	v_lshl_add_u64 v[64:65], v[64:65], 1, s[84:85]
	v_addc_co_u32_e32 v69, vcc, 0, v67, vcc
	global_load_dword v112, v[66:67], off
	global_load_ushort v105, v[64:65], off
	global_load_dword v181, v[68:69], off offset:-4096
	global_load_ushort v106, v[64:65], off offset:2048
	global_load_dword v182, v[68:69], off
	v_add_co_u32_e32 v68, vcc, s70, v64
	s_lshl_b64 s[54:55], s[2:3], 2
	s_nop 0
	v_addc_co_u32_e32 v69, vcc, 0, v65, vcc
	v_add_co_u32_e32 v70, vcc, s33, v64
	s_nop 1
	v_addc_co_u32_e32 v71, vcc, 0, v65, vcc
	v_add_co_u32_e32 v72, vcc, s5, v66
	global_load_ushort v107, v[70:71], off offset:-4096
	s_nop 0
	v_addc_co_u32_e32 v73, vcc, 0, v67, vcc
	global_load_dword v184, v[72:73], off offset:-4096
	global_load_ushort v108, v[68:69], off offset:2048
	global_load_dword v186, v[72:73], off
	global_load_ushort v109, v[70:71], off
	v_add_co_u32_e32 v68, vcc, s88, v66
	s_nop 1
	v_addc_co_u32_e32 v69, vcc, 0, v67, vcc
	global_load_dword v188, v[68:69], off offset:-4096
	global_load_ushort v110, v[70:71], off offset:2048
	global_load_dword v190, v[68:69], off
	v_add_co_u32_e32 v68, vcc, s78, v64
	s_nop 1
	v_addc_co_u32_e32 v69, vcc, 0, v65, vcc
	v_add_co_u32_e32 v70, vcc, s5, v64
	s_nop 1
	v_addc_co_u32_e32 v71, vcc, 0, v65, vcc
	v_add_co_u32_e32 v72, vcc, s81, v66
	global_load_ushort v111, v[70:71], off offset:-4096
	s_nop 0
	v_addc_co_u32_e32 v73, vcc, 0, v67, vcc
	global_load_dword v192, v[72:73], off offset:-4096
	global_load_ushort v113, v[68:69], off offset:2048
	global_load_dword v195, v[72:73], off
	global_load_ushort v159, v[70:71], off
	v_add_co_u32_e32 v68, vcc, s59, v66
	s_nop 1
	v_addc_co_u32_e32 v69, vcc, 0, v67, vcc
	global_load_dword v196, v[68:69], off offset:-4096
	global_load_ushort v183, v[70:71], off offset:2048
	global_load_dword v198, v[68:69], off
	v_add_co_u32_e32 v68, vcc, s79, v64
	s_nop 1
	v_addc_co_u32_e32 v69, vcc, 0, v65, vcc
	v_add_co_u32_e32 v70, vcc, s88, v64
	s_nop 1
	v_addc_co_u32_e32 v71, vcc, 0, v65, vcc
	v_add_co_u32_e32 v72, vcc, s67, v66
	global_load_ushort v185, v[70:71], off offset:-4096
	s_nop 0
	v_addc_co_u32_e32 v73, vcc, 0, v67, vcc
	global_load_dword v200, v[72:73], off offset:-4096
	global_load_ushort v187, v[68:69], off offset:2048
	global_load_dword v201, v[72:73], off
	global_load_ushort v189, v[70:71], off
	v_add_co_u32_e32 v68, vcc, s75, v66
	s_nop 1
	v_addc_co_u32_e32 v69, vcc, 0, v67, vcc
	v_add_co_u32_e32 v64, vcc, s80, v64
	global_load_dword v202, v[68:69], off offset:-4096
	global_load_ushort v191, v[70:71], off offset:2048
	global_load_dword v203, v[68:69], off
	v_addc_co_u32_e32 v65, vcc, 0, v65, vcc
	v_add_co_u32_e32 v66, vcc, s64, v66
	global_load_ushort v194, v[64:65], off
	s_nop 0
	v_addc_co_u32_e32 v67, vcc, 0, v67, vcc
	global_load_dword v199, v[66:67], off
	global_load_ushort v197, v[64:65], off offset:2048
	ds_read_b128 v[64:67], v171 offset:25600
	ds_read_b128 v[68:71], v171 offset:16896
	ds_read_b128 v[88:91], v171 offset:16928
	ds_read_b128 v[92:95], v171 offset:25632
	s_waitcnt lgkmcnt(2)
	v_mfma_f32_32x32x16_bf16 v[64:79], v[64:67], v[68:71], 0
	s_waitcnt lgkmcnt(0)
	v_mfma_f32_32x32x16_bf16 v[64:79], v[92:95], v[88:91], v[64:79]
	ds_read_b128 v[88:91], v171 offset:25664
	ds_read_b128 v[92:95], v171 offset:16960
	s_waitcnt lgkmcnt(0)
	v_mfma_f32_32x32x16_bf16 v[64:79], v[88:91], v[92:95], v[64:79]
	ds_read_b128 v[88:91], v171 offset:25696
	ds_read_b128 v[92:95], v171 offset:16992
	s_waitcnt lgkmcnt(0)
	v_mfma_f32_32x32x16_bf16 v[64:79], v[88:91], v[92:95], v[64:79]
	ds_read_b128 v[88:91], v171 offset:25728
	ds_read_b128 v[92:95], v171 offset:17024
	s_waitcnt lgkmcnt(0)
	v_mfma_f32_32x32x16_bf16 v[64:79], v[88:91], v[92:95], v[64:79]
	ds_read_b128 v[88:91], v171 offset:25760
	ds_read_b128 v[92:95], v171 offset:17056
	s_waitcnt lgkmcnt(0)
	v_mfma_f32_32x32x16_bf16 v[64:79], v[88:91], v[92:95], v[64:79]
	ds_read_b128 v[88:91], v171 offset:25792
	ds_read_b128 v[92:95], v171 offset:17088
	s_waitcnt lgkmcnt(0)
	v_mfma_f32_32x32x16_bf16 v[64:79], v[88:91], v[92:95], v[64:79]
	ds_read_b128 v[88:91], v171 offset:25824
	ds_read_b128 v[92:95], v171 offset:17120
	s_waitcnt lgkmcnt(0)
	v_mfma_f32_32x32x16_bf16 v[64:79], v[88:91], v[92:95], v[64:79]
	s_nop 11
	v_cndmask_b32_e64 v88, v64, 0, s[10:11]
	v_cndmask_b32_e64 v92, v88, v64, s[12:13]
	v_cndmask_b32_e64 v93, 0, v65, s[12:13]
	v_cndmask_b32_e64 v94, v66, 0, s[14:15]
	v_cndmask_b32_e64 v95, v67, 0, s[16:17]
	v_cndmask_b32_e64 v96, v68, 0, s[18:19]
	v_cndmask_b32_e64 v97, v69, 0, s[20:21]
	v_cndmask_b32_e64 v98, v70, 0, s[22:23]
	v_cndmask_b32_e64 v71, v71, 0, s[24:25]
	v_add_u32_e32 v68, 0xa800, v175
	ds_read2_b64 v[64:67], v68 offset0:192 offset1:194
	ds_read2_b64 v[88:91], v68 offset0:196 offset1:198
	v_cvt_pk_bf16_f32 v68, v92, v93
	v_cvt_pk_bf16_f32 v69, v94, v95
	v_cvt_pk_bf16_f32 v70, v96, v97
	v_cvt_pk_bf16_f32 v71, v98, v71
	v_cndmask_b32_e64 v99, v72, 0, s[26:27]
	v_cndmask_b32_e64 v100, v73, 0, s[28:29]
	v_cndmask_b32_e64 v101, v74, 0, s[30:31]
	v_cndmask_b32_e64 v102, v75, 0, s[34:35]
	v_cndmask_b32_e64 v103, v76, 0, s[36:37]
	v_cndmask_b32_e64 v104, v77, 0, s[38:39]
	v_cndmask_b32_e64 v204, v78, 0, s[40:41]
	v_cndmask_b32_e64 v205, v79, 0, s[42:43]
	s_waitcnt lgkmcnt(1)
	v_mfma_f32_32x32x16_bf16 v[64:79], v[68:71], v[64:67], 0
	v_cvt_pk_bf16_f32 v92, v99, v100
	v_cvt_pk_bf16_f32 v93, v101, v102
	v_cvt_pk_bf16_f32 v94, v103, v104
	v_cvt_pk_bf16_f32 v95, v204, v205
	v_add_u32_e32 v100, 0x4000, v176
	v_cvt_pk_bf16_f32 v96, v0, v1
	v_cvt_pk_bf16_f32 v97, v2, v3
	s_waitcnt lgkmcnt(0)
	v_mfma_f32_32x32x16_bf16 v[64:79], v[92:95], v[88:91], v[64:79]
	ds_read2_b64 v[88:91], v100 offset0:64 offset1:66
	ds_read2_b64 v[92:95], v100 offset0:68 offset1:70
	v_cvt_pk_bf16_f32 v98, v4, v5
	v_cvt_pk_bf16_f32 v99, v6, v7
	s_waitcnt lgkmcnt(1)
	s_nop 0
	v_mfma_f32_32x32x16_bf16 v[64:79], v[88:91], v[96:99], v[64:79]
	v_cvt_pk_bf16_f32 v88, v8, v9
	v_cvt_pk_bf16_f32 v89, v10, v11
	v_cvt_pk_bf16_f32 v90, v12, v13
	v_cvt_pk_bf16_f32 v91, v14, v15
	s_waitcnt lgkmcnt(0)
	s_nop 0
	v_mfma_f32_32x32x16_bf16 v[64:79], v[92:95], v[88:91], v[64:79]
	ds_read2_b64 v[88:91], v100 offset0:72 offset1:74
	v_cvt_pk_bf16_f32 v92, v16, v17
	v_cvt_pk_bf16_f32 v93, v18, v19
	v_cvt_pk_bf16_f32 v94, v20, v21
	v_cvt_pk_bf16_f32 v95, v22, v23
	s_waitcnt lgkmcnt(0)
	s_nop 0
	v_mfma_f32_32x32x16_bf16 v[64:79], v[88:91], v[92:95], v[64:79]
	ds_read2_b64 v[88:91], v100 offset0:76 offset1:78
	v_cvt_pk_bf16_f32 v92, v24, v25
	v_cvt_pk_bf16_f32 v93, v26, v27
	v_cvt_pk_bf16_f32 v94, v28, v29
	v_cvt_pk_bf16_f32 v95, v30, v31
	s_waitcnt lgkmcnt(0)
	s_nop 0
	v_mfma_f32_32x32x16_bf16 v[64:79], v[88:91], v[92:95], v[64:79]
	ds_read2_b64 v[88:91], v100 offset0:80 offset1:82
	v_cvt_pk_bf16_f32 v92, v32, v33
	v_cvt_pk_bf16_f32 v93, v34, v35
	v_cvt_pk_bf16_f32 v94, v36, v37
	v_cvt_pk_bf16_f32 v95, v38, v39
	s_waitcnt lgkmcnt(0)
	s_nop 0
	v_mfma_f32_32x32x16_bf16 v[64:79], v[88:91], v[92:95], v[64:79]
	ds_read2_b64 v[88:91], v100 offset0:84 offset1:86
	v_cvt_pk_bf16_f32 v92, v40, v41
	v_cvt_pk_bf16_f32 v93, v42, v43
	v_cvt_pk_bf16_f32 v94, v44, v45
	v_cvt_pk_bf16_f32 v95, v46, v47
	s_waitcnt lgkmcnt(0)
	s_nop 0
	v_mfma_f32_32x32x16_bf16 v[64:79], v[88:91], v[92:95], v[64:79]
	ds_read2_b64 v[88:91], v100 offset0:88 offset1:90
	v_cvt_pk_bf16_f32 v92, v48, v49
	v_cvt_pk_bf16_f32 v93, v50, v51
	v_cvt_pk_bf16_f32 v94, v52, v53
	v_cvt_pk_bf16_f32 v95, v54, v55
	s_waitcnt lgkmcnt(0)
	s_nop 0
	v_mfma_f32_32x32x16_bf16 v[64:79], v[88:91], v[92:95], v[64:79]
	ds_read2_b64 v[88:91], v100 offset0:92 offset1:94
	v_cvt_pk_bf16_f32 v92, v56, v57
	v_cvt_pk_bf16_f32 v93, v58, v59
	v_cvt_pk_bf16_f32 v94, v60, v61
	v_cvt_pk_bf16_f32 v95, v62, v63
	s_waitcnt lgkmcnt(0)
	s_nop 0
	v_mfma_f32_32x32x16_bf16 v[64:79], v[88:91], v[92:95], v[64:79]
	ds_read_b128 v[88:91], v170 offset:55808
	ds_read_b128 v[92:95], v170 offset:55840
	ds_read_b128 v[96:99], v170 offset:55872
	ds_read_b128 v[100:103], v170 offset:55904
	s_waitcnt lgkmcnt(3)
	v_pk_mul_f32 v[2:3], v[2:3], v[90:91]
	s_waitcnt lgkmcnt(2)
	v_pk_mul_f32 v[6:7], v[6:7], v[94:95]
	s_waitcnt lgkmcnt(1)
	v_pk_mul_f32 v[10:11], v[10:11], v[98:99]
	s_waitcnt lgkmcnt(0)
	v_pk_mul_f32 v[14:15], v[14:15], v[102:103]
	v_pk_mul_f32 v[12:13], v[12:13], v[100:101]
	v_pk_mul_f32 v[8:9], v[8:9], v[96:97]
	v_pk_mul_f32 v[4:5], v[4:5], v[92:93]
	v_pk_mul_f32 v[0:1], v[0:1], v[88:89]
	ds_read_b128 v[96:99], v177 offset:34304
	ds_read_b128 v[100:103], v177 offset:34336
	ds_read_b128 v[88:91], v172 offset:44544
	ds_read_b128 v[92:95], v172 offset:44576
	s_waitcnt lgkmcnt(1)
	v_mfma_f32_32x32x16_bf16 v[0:15], v[96:99], v[88:91], v[0:15]
	s_waitcnt lgkmcnt(0)
	v_mfma_f32_32x32x16_bf16 v[0:15], v[100:103], v[92:95], v[0:15]
	ds_read_b128 v[96:99], v170 offset:55936
	ds_read_b128 v[100:103], v170 offset:55968
	ds_read_b128 v[204:207], v170 offset:56000
	ds_read_b128 v[208:211], v170 offset:56032
	s_waitcnt lgkmcnt(3)
	v_pk_mul_f32 v[18:19], v[18:19], v[98:99]
	v_pk_mul_f32 v[16:17], v[16:17], v[96:97]
	ds_read_b128 v[96:99], v177 offset:36864
	s_waitcnt lgkmcnt(1)
	v_pk_mul_f32 v[30:31], v[30:31], v[210:211]
	v_pk_mul_f32 v[26:27], v[26:27], v[206:207]
	v_pk_mul_f32 v[22:23], v[22:23], v[102:103]
	v_pk_mul_f32 v[28:29], v[28:29], v[208:209]
	v_pk_mul_f32 v[24:25], v[24:25], v[204:205]
	v_pk_mul_f32 v[20:21], v[20:21], v[100:101]
	s_waitcnt lgkmcnt(0)
	s_nop 0
	v_mfma_f32_32x32x16_bf16 v[16:31], v[96:99], v[88:91], v[16:31]
	ds_read_b128 v[96:99], v177 offset:36896
	s_waitcnt lgkmcnt(0)
	v_mfma_f32_32x32x16_bf16 v[16:31], v[96:99], v[92:95], v[16:31]
	ds_read_b128 v[96:99], v170 offset:56064
	ds_read_b128 v[100:103], v170 offset:56096
	ds_read_b128 v[204:207], v170 offset:56128
	ds_read_b128 v[208:211], v170 offset:56160
	s_waitcnt lgkmcnt(3)
	v_pk_mul_f32 v[34:35], v[34:35], v[98:99]
	v_pk_mul_f32 v[32:33], v[32:33], v[96:97]
	ds_read_b128 v[96:99], v177 offset:39424
	s_waitcnt lgkmcnt(1)
	v_pk_mul_f32 v[46:47], v[46:47], v[210:211]
	v_pk_mul_f32 v[42:43], v[42:43], v[206:207]
	v_pk_mul_f32 v[38:39], v[38:39], v[102:103]
	v_pk_mul_f32 v[44:45], v[44:45], v[208:209]
	v_pk_mul_f32 v[40:41], v[40:41], v[204:205]
	v_pk_mul_f32 v[36:37], v[36:37], v[100:101]
	s_waitcnt lgkmcnt(0)
	s_nop 0
	v_mfma_f32_32x32x16_bf16 v[32:47], v[96:99], v[88:91], v[32:47]
	ds_read_b128 v[96:99], v177 offset:39456
	s_waitcnt lgkmcnt(0)
	v_mfma_f32_32x32x16_bf16 v[32:47], v[96:99], v[92:95], v[32:47]
	ds_read_b128 v[96:99], v170 offset:56192
	ds_read_b128 v[100:103], v170 offset:56224
	ds_read_b128 v[204:207], v170 offset:56256
	ds_read_b128 v[208:211], v170 offset:56288
	s_waitcnt lgkmcnt(3)
	v_pk_mul_f32 v[50:51], v[50:51], v[98:99]
	v_pk_mul_f32 v[48:49], v[48:49], v[96:97]
	ds_read_b128 v[96:99], v177 offset:41984
	s_waitcnt lgkmcnt(1)
	v_pk_mul_f32 v[62:63], v[62:63], v[210:211]
	v_pk_mul_f32 v[58:59], v[58:59], v[206:207]
	v_pk_mul_f32 v[54:55], v[54:55], v[102:103]
	v_pk_mul_f32 v[60:61], v[60:61], v[208:209]
	v_pk_mul_f32 v[56:57], v[56:57], v[204:205]
	v_pk_mul_f32 v[52:53], v[52:53], v[100:101]
	v_lshlrev_b32_e32 v100, 2, v120
	s_waitcnt lgkmcnt(0)
	v_mfma_f32_32x32x16_bf16 v[48:63], v[96:99], v[88:91], v[48:63]
	ds_read_b128 v[88:91], v177 offset:42016
	ds_write_b32 v178, v64
	ds_write2_b32 v179, v65, v66 offset1:132
	ds_write_b32 v179, v67 offset:1056
	v_add_u32_e32 v64, 0xe00, v179
	ds_write2_b32 v64, v68, v69 offset0:28 offset1:160
	v_add_u32_e32 v64, 0x1200, v179
	ds_write2_b32 v64, v70, v71 offset0:36 offset1:168
	v_add_u32_e32 v64, 0x1e00, v179
	ds_write2_b32 v64, v72, v73 offset0:60 offset1:192
	v_add_u32_e32 v64, 0x2200, v179
	ds_write2_b32 v64, v74, v75 offset0:68 offset1:200
	v_add_u32_e32 v64, 0x2e00, v179
	ds_write2_b32 v64, v76, v77 offset0:92 offset1:224
	v_add_u32_e32 v64, 0x3200, v179
	ds_write2_b32 v64, v78, v79 offset0:100 offset1:232
	s_waitcnt lgkmcnt(0)
	s_barrier
	ds_read_b128 v[76:79], v180
	ds_read_b128 v[72:75], v180 offset:16
	ds_read_b128 v[68:71], v180 offset:32
	ds_read_b128 v[64:67], v180 offset:48
	s_waitcnt lgkmcnt(13)
	v_mfma_f32_32x32x16_bf16 v[48:63], v[88:91], v[92:95], v[48:63]
	s_waitcnt lgkmcnt(3)
	v_mov_b32_e32 v90, v77
	s_waitcnt lgkmcnt(2)
	v_mov_b32_e32 v91, v73
	v_mov_b32_e32 v88, v76
	v_mov_b32_e32 v89, v72
	v_pk_mul_f32 v[90:91], v[90:91], v[90:91]
	s_waitcnt lgkmcnt(1)
	v_mov_b32_e32 v92, v69
	v_pk_fma_f32 v[88:89], v[88:89], v[88:89], v[90:91]
	v_mov_b32_e32 v90, v78
	v_mov_b32_e32 v91, v74
	v_pk_fma_f32 v[88:89], v[90:91], v[90:91], v[88:89]
	v_mov_b32_e32 v90, v79
	v_mov_b32_e32 v91, v75
	s_waitcnt lgkmcnt(0)
	v_mov_b32_e32 v93, v65
	v_pk_fma_f32 v[88:89], v[90:91], v[90:91], v[88:89]
	v_mov_b32_e32 v90, v68
	v_mov_b32_e32 v91, v64
	v_pk_mul_f32 v[92:93], v[92:93], v[92:93]
	v_add_f32_e32 v88, v88, v89
	v_pk_fma_f32 v[90:91], v[90:91], v[90:91], v[92:93]
	v_mov_b32_e32 v92, v70
	v_mov_b32_e32 v93, v66
	v_pk_fma_f32 v[90:91], v[92:93], v[92:93], v[90:91]
	v_mov_b32_e32 v92, v71
	v_mov_b32_e32 v93, v67
	v_pk_fma_f32 v[90:91], v[92:93], v[92:93], v[90:91]
	v_xor_b32_e32 v89, 1, v232
	v_add_f32_e32 v88, v88, v90
	v_and_b32_e32 v90, 64, v232
	v_add_u32_e32 v90, 64, v90
	v_cmp_lt_i32_e32 vcc, v89, v90
	v_add_f32_e32 v88, v88, v91
	s_load_dwordx2 s[48:49], s[0:1], 0x70
	v_cndmask_b32_e32 v89, v232, v89, vcc
	v_lshlrev_b32_e32 v89, 2, v89
	ds_bpermute_b32 v89, v89, v88
	s_waitcnt lgkmcnt(0)
	s_add_u32 s48, s48, s54
	s_addc_u32 s49, s49, s55
	s_add_u32 s44, s44, 0x10000
	v_add_f32_e32 v88, v88, v89
	v_xor_b32_e32 v89, 2, v232
	v_cmp_lt_i32_e32 vcc, v89, v90
	s_addc_u32 s45, s45, 0
	s_add_i32 s52, s52, 32
	v_cndmask_b32_e32 v89, v232, v89, vcc
	v_lshlrev_b32_e32 v89, 2, v89
	ds_bpermute_b32 v89, v89, v88
	s_cmp_eq_u32 s44, 0x80000
	s_waitcnt lgkmcnt(0)
	v_add_f32_e32 v88, v88, v89
	v_xor_b32_e32 v89, 4, v232
	v_cmp_lt_i32_e32 vcc, v89, v90
	s_nop 1
	v_cndmask_b32_e32 v89, v232, v89, vcc
	v_lshlrev_b32_e32 v89, 2, v89
	ds_bpermute_b32 v89, v89, v88
	s_waitcnt lgkmcnt(0)
	v_add_f32_e32 v88, v88, v89
	v_fmamk_f32 v88, v88, 0x3c000000, v226
	v_cmp_gt_f32_e32 vcc, s87, v88
	v_mul_f32_e32 v89, 0x4b800000, v88
	s_nop 0
	v_cndmask_b32_e32 v88, v88, v89, vcc
	v_rsq_f32_e32 v88, v88
	s_nop 0
	v_mul_f32_e32 v89, 0x45800000, v88
	v_cndmask_b32_e32 v104, v88, v89, vcc
	s_waitcnt vmcnt(32)
	v_pk_mul_f32 v[76:77], v[76:77], v[104:105] op_sel_hi:[1,0]
	v_pk_mul_f32 v[78:79], v[78:79], v[104:105] op_sel_hi:[1,0]
	v_pk_mul_f32 v[72:73], v[72:73], v[104:105] op_sel_hi:[1,0]
	v_pk_mul_f32 v[68:69], v[68:69], v[104:105] op_sel_hi:[1,0]
	v_pk_mul_f32 v[70:71], v[70:71], v[104:105] op_sel_hi:[1,0]
	v_pk_mul_f32 v[64:65], v[64:65], v[104:105] op_sel_hi:[1,0]
	s_mov_b32 s48, 0x8be9000
	v_pk_mul_f32 v[64:65], v[248:249], v[64:65]
	v_pk_mul_f32 v[68:69], v[244:245], v[68:69]
	v_pk_mul_f32 v[72:73], v[216:217], v[72:73]
	v_pk_mul_f32 v[76:77], v[212:213], v[76:77]
	v_lshlrev_b32_e32 v100, 16, v84
	v_and_b32_e32 v101, 0xffff0000, v84
	v_pk_mul_f32 v[78:79], v[214:215], v[78:79]
	v_lshlrev_b32_e32 v84, 16, v85
	v_and_b32_e32 v85, 0xffff0000, v85
	v_pk_mul_f32 v[76:77], v[76:77], v[100:101]
	v_pk_mul_f32 v[78:79], v[78:79], v[84:85]
	v_cvt_pk_bf16_f32 v76, v76, v77
	v_cvt_pk_bf16_f32 v77, v78, v79
	v_lshlrev_b32_e32 v78, 16, v86
	v_and_b32_e32 v79, 0xffff0000, v86
	v_pk_mul_f32 v[72:73], v[72:73], v[78:79]
	v_pk_mul_f32 v[70:71], v[246:247], v[70:71]
	v_cvt_pk_bf16_f32 v78, v72, v73
	v_pk_mul_f32 v[72:73], v[74:75], v[104:105] op_sel_hi:[1,0]
	v_lshlrev_b32_e32 v74, 16, v87
	v_pk_mul_f32 v[72:73], v[218:219], v[72:73]
	v_and_b32_e32 v75, 0xffff0000, v87
	v_pk_mul_f32 v[72:73], v[72:73], v[74:75]
	s_nop 0
	v_cvt_pk_bf16_f32 v79, v72, v73
	v_lshlrev_b32_e32 v72, 16, v80
	v_and_b32_e32 v73, 0xffff0000, v80
	v_pk_mul_f32 v[68:69], v[68:69], v[72:73]
	v_lshlrev_b32_e32 v72, 16, v81
	v_and_b32_e32 v73, 0xffff0000, v81
	v_pk_mul_f32 v[70:71], v[70:71], v[72:73]
	v_cvt_pk_bf16_f32 v68, v68, v69
	v_cvt_pk_bf16_f32 v69, v70, v71
	v_lshlrev_b32_e32 v70, 16, v82
	v_and_b32_e32 v71, 0xffff0000, v82
	v_pk_mul_f32 v[64:65], v[64:65], v[70:71]
	s_nop 0
	v_cvt_pk_bf16_f32 v70, v64, v65
	v_pk_mul_f32 v[64:65], v[66:67], v[104:105] op_sel_hi:[1,0]
	v_lshlrev_b32_e32 v66, 16, v83
	v_pk_mul_f32 v[64:65], v[250:251], v[64:65]
	v_and_b32_e32 v67, 0xffff0000, v83
	v_pk_mul_f32 v[64:65], v[64:65], v[66:67]
	s_nop 0
	v_cvt_pk_bf16_f32 v71, v64, v65
	v_add_co_u32_e32 v64, vcc, s48, v166
	s_nop 1
	v_addc_co_u32_e32 v65, vcc, 0, v167, vcc
	global_store_dwordx4 v[64:65], v[76:79], off
	global_store_dwordx4 v[64:65], v[68:71], off offset:16
	s_cbranch_scc1 .LBB0_152
.LBB0_142:
	v_lshl_add_u64 v[166:167], v[164:165], 0, s[44:45]
	s_mov_b64 s[48:49], 0xac69000
	v_lshl_add_u64 v[64:65], v[166:167], 0, s[48:49]
	s_mov_b32 s48, 0xac69000
	v_add_co_u32_e32 v66, vcc, s48, v166
	s_mov_b64 s[48:49], 0x10de9000
	s_nop 0
	v_addc_co_u32_e32 v67, vcc, 0, v167, vcc
	v_lshl_add_u64 v[72:73], v[166:167], 0, s[48:49]
	s_mov_b32 s48, 0x10de9000
	v_add_co_u32_e32 v74, vcc, s48, v166
	global_load_dwordx4 v[68:71], v[66:67], off
	s_nop 0
	global_load_dwordx4 v[64:67], v[64:65], off offset:16
	v_addc_co_u32_e32 v75, vcc, 0, v167, vcc
	global_load_dwordx4 v[84:87], v[74:75], off
	global_load_dwordx4 v[80:83], v[72:73], off offset:16
	s_waitcnt vmcnt(35)
	v_add_f32_e32 v72, 0, v112
	s_waitcnt vmcnt(33)
	v_add_f32_e32 v76, v72, v181
	s_waitcnt vmcnt(31)
	v_add_f32_e32 v88, v76, v182
	s_waitcnt vmcnt(29)
	v_add_f32_e32 v89, v88, v184
	s_waitcnt vmcnt(27)
	v_add_f32_e32 v90, v89, v186
	s_waitcnt vmcnt(25)
	v_add_f32_e32 v91, v90, v188
	s_waitcnt vmcnt(23)
	v_add_f32_e32 v92, v91, v190
	s_waitcnt vmcnt(21)
	v_add_f32_e32 v93, v92, v192
	s_waitcnt vmcnt(19)
	v_add_f32_e32 v94, v93, v195
	s_waitcnt vmcnt(17)
	v_add_f32_e32 v95, v94, v196
	s_waitcnt vmcnt(15)
	v_add_f32_e32 v96, v95, v198
	s_waitcnt vmcnt(13)
	v_add_f32_e32 v97, v96, v200
	s_waitcnt vmcnt(11)
	v_add_f32_e32 v98, v97, v201
	s_waitcnt vmcnt(9)
	v_add_f32_e32 v99, v98, v202
	s_waitcnt vmcnt(7)
	v_add_f32_e32 v100, v99, v203
	s_waitcnt vmcnt(5)
	v_add_f32_e32 v73, v100, v199
	ds_write_b32 v117, v73 offset:54784
	s_waitcnt lgkmcnt(0)
	s_barrier
	ds_read2st64_b32 v[74:75], v119 offset0:214 offset1:216
	v_exp_f32_e32 v78, v112
	v_exp_f32_e32 v79, v181
	s_waitcnt lgkmcnt(0)
	v_cndmask_b32_e64 v77, v74, 0, s[6:7]
	v_add_f32_e32 v101, v72, v77
	v_add_f32_e32 v103, v88, v77
	v_add_f32_e32 v104, v89, v77
	v_add_u32_e32 v72, 0x400, v174
	ds_write2_b32 v72, v103, v104 offset0:8 offset1:140
	v_add_f32_e32 v112, v90, v77
	v_add_f32_e32 v181, v91, v77
	v_add_u32_e32 v72, 0x800, v174
	v_exp_f32_e32 v88, v182
	v_exp_f32_e32 v89, v184
	ds_write2_b32 v72, v112, v181 offset0:16 offset1:148
	v_add_f32_e32 v182, v92, v77
	v_add_f32_e32 v184, v93, v77
	v_add_u32_e32 v72, 0xc00, v174
	v_exp_f32_e32 v90, v186
	v_exp_f32_e32 v91, v188
	ds_write2_b32 v72, v182, v184 offset0:24 offset1:156
	v_add_f32_e32 v186, v94, v77
	v_add_f32_e32 v188, v95, v77
	v_add_u32_e32 v72, 0x1000, v174
	v_exp_f32_e32 v92, v190
	v_exp_f32_e32 v93, v192
	ds_write2_b32 v72, v186, v188 offset0:32 offset1:164
	v_add_f32_e32 v190, v96, v77
	v_add_f32_e32 v192, v97, v77
	v_add_u32_e32 v72, 0x1400, v174
	v_exp_f32_e32 v94, v195
	v_exp_f32_e32 v95, v196
	ds_write2_b32 v72, v190, v192 offset0:40 offset1:172
	v_add_f32_e32 v195, v98, v77
	v_add_f32_e32 v196, v99, v77
	v_add_u32_e32 v72, 0x1800, v174
	v_add_f32_e32 v102, v76, v77
	ds_write2_b32 v72, v195, v196 offset0:48 offset1:180
	v_mov_b32_e32 v72, v74
	v_mov_b32_e32 v76, v75
	v_pk_add_f32 v[72:73], v[72:73], v[76:77]
	ds_write2_b32 v174, v101, v102 offset1:132
	v_sub_f32_e32 v74, v72, v101
	v_sub_f32_e32 v75, v72, v102
	v_exp_f32_e32 v74, v74
	v_exp_f32_e32 v75, v75
	v_add_f32_e32 v101, v100, v77
	v_pk_add_f32 v[76:77], v[78:79], 1.0 op_sel_hi:[1,0] neg_lo:[1,0] neg_hi:[1,0]
	v_sub_f32_e32 v78, v72, v112
	v_pk_mul_f32 v[74:75], v[76:77], v[74:75]
	v_sub_f32_e32 v76, v72, v103
	v_sub_f32_e32 v77, v72, v104
	v_exp_f32_e32 v76, v76
	v_exp_f32_e32 v77, v77
	v_sub_f32_e32 v79, v72, v181
	v_exp_f32_e32 v78, v78
	v_exp_f32_e32 v79, v79
	v_pk_add_f32 v[88:89], v[88:89], 1.0 op_sel_hi:[1,0] neg_lo:[1,0] neg_hi:[1,0]
	v_pk_add_f32 v[92:93], v[92:93], 1.0 op_sel_hi:[1,0] neg_lo:[1,0] neg_hi:[1,0]
	v_pk_mul_f32 v[76:77], v[88:89], v[76:77]
	v_pk_add_f32 v[88:89], v[90:91], 1.0 op_sel_hi:[1,0] neg_lo:[1,0] neg_hi:[1,0]
	v_sub_f32_e32 v90, v72, v186
	v_pk_mul_f32 v[78:79], v[88:89], v[78:79]
	v_sub_f32_e32 v88, v72, v182
	v_sub_f32_e32 v89, v72, v184
	v_exp_f32_e32 v88, v88
	v_exp_f32_e32 v89, v89
	v_sub_f32_e32 v91, v72, v188
	v_exp_f32_e32 v90, v90
	v_exp_f32_e32 v91, v91
	v_pk_mul_f32 v[88:89], v[92:93], v[88:89]
	v_pk_add_f32 v[92:93], v[94:95], 1.0 op_sel_hi:[1,0] neg_lo:[1,0] neg_hi:[1,0]
	v_exp_f32_e32 v96, v198
	v_exp_f32_e32 v97, v200
	v_pk_mul_f32 v[90:91], v[92:93], v[90:91]
	v_sub_f32_e32 v92, v72, v190
	v_sub_f32_e32 v93, v72, v192
	v_exp_f32_e32 v98, v201
	v_exp_f32_e32 v99, v202
	v_exp_f32_e32 v92, v92
	v_exp_f32_e32 v93, v93
	v_sub_f32_e32 v94, v72, v195
	v_sub_f32_e32 v95, v72, v196
	v_exp_f32_e32 v94, v94
	v_exp_f32_e32 v95, v95
	v_pk_add_f32 v[96:97], v[96:97], 1.0 op_sel_hi:[1,0] neg_lo:[1,0] neg_hi:[1,0]
	v_exp_f32_e32 v100, v203
	v_pk_mul_f32 v[92:93], v[96:97], v[92:93]
	v_pk_add_f32 v[96:97], v[98:99], 1.0 op_sel_hi:[1,0] neg_lo:[1,0] neg_hi:[1,0]
	v_cvt_pk_bf16_f32 v74, v74, v75
	v_pk_mul_f32 v[94:95], v[96:97], v[94:95]
	v_add_u32_e32 v97, 0x1c00, v174
	v_sub_f32_e32 v96, v72, v101
	ds_write2_b32 v97, v101, v73 offset0:56 offset1:188
	v_exp_f32_e32 v101, v199
	v_sub_f32_e32 v73, v72, v73
	v_exp_f32_e32 v96, v96
	v_exp_f32_e32 v97, v73
	v_cvt_pk_bf16_f32 v75, v76, v77
	v_cvt_pk_bf16_f32 v76, v78, v79
	v_pk_add_f32 v[78:79], v[100:101], 1.0 op_sel_hi:[1,0] neg_lo:[1,0] neg_hi:[1,0]
	v_cvt_pk_bf16_f32 v77, v88, v89
	v_pk_mul_f32 v[78:79], v[78:79], v[96:97]
	ds_write_b128 v121, v[74:77] offset:34304
	v_cvt_pk_bf16_f32 v74, v90, v91
	v_cvt_pk_bf16_f32 v75, v92, v93
	v_cvt_pk_bf16_f32 v76, v94, v95
	v_cvt_pk_bf16_f32 v77, v78, v79
	ds_write_b128 v121, v[74:77] offset:34320
	v_lshl_or_b32 v74, v106, 16, v105
	v_lshl_or_b32 v75, v108, 16, v107
	v_lshl_or_b32 v76, v110, 16, v109
	v_lshl_or_b32 v77, v113, 16, v111
	ds_write_b128 v121, v[74:77] offset:44544
	v_lshl_or_b32 v74, v183, 16, v159
	v_lshl_or_b32 v75, v187, 16, v185
	v_lshl_or_b32 v76, v191, 16, v189
	s_waitcnt vmcnt(4)
	v_lshl_or_b32 v77, v197, 16, v194
	ds_write_b128 v121, v[74:77] offset:44560
	s_and_saveexec_b64 s[48:49], s[6:7]
	v_exp_f32_e32 v72, v72
	ds_write_b32 v119, v72 offset:55808
	s_or_b64 exec, exec, s[48:49]
	s_waitcnt lgkmcnt(0)
	s_barrier
	ds_read_b128 v[88:91], v163
	v_mov_b32_e32 v98, 0
	v_mov_b32_e32 v94, 0
	v_mov_b32_e32 v95, 0
	v_mov_b32_e32 v96, 0
	v_mov_b32_e32 v97, 0
	s_and_saveexec_b64 s[48:49], s[8:9]
	ds_read_b128 v[94:97], v168
	s_or_b64 exec, exec, s[48:49]
	ds_read_b128 v[102:105], v163 offset:16
	v_mov_b32_e32 v99, 0
	v_mov_b32_e32 v100, 0
	v_mov_b32_e32 v101, 0
	s_and_saveexec_b64 s[48:49], s[8:9]
	ds_read_b128 v[98:101], v168 offset:16
	s_or_b64 exec, exec, s[48:49]
	ds_read_b128 v[106:109], v163 offset:32
	v_mov_b32_e32 v72, 0
	v_mov_b32_e32 v110, 0
	v_mov_b32_e32 v111, 0
	v_mov_b32_e32 v112, 0
	v_mov_b32_e32 v113, 0
	s_and_saveexec_b64 s[48:49], s[8:9]
	ds_read_b128 v[110:113], v168 offset:32
	s_or_b64 exec, exec, s[48:49]
	ds_read_b128 v[76:79], v163 offset:48
	v_mov_b32_e32 v73, 0
	v_mov_b32_e32 v74, 0
	v_mov_b32_e32 v75, 0
	s_and_saveexec_b64 s[48:49], s[8:9]
	s_cbranch_execz .LBB0_141
	ds_read_b128 v[72:75], v168 offset:48
	s_branch .LBB0_141

.LBB0_1147:
	v_mov_b32_e32 v0, v220
	s_load_dwordx2 s[8:9], s[0:1], 0x48
	v_and_b32_e32 v2, 63, v0
	v_lshlrev_b32_e32 v192, 4, v2
	s_waitcnt lgkmcnt(0)
	v_lshl_add_u64 v[0:1], s[16:17], 0, v[192:193]
	s_add_u32 s2, s16, 0x1b06c790
	v_lshl_add_u64 v[66:67], s[8:9], 0, v[192:193]
	s_mov_b64 s[8:9], 0x5d01000
	v_lshl_add_u64 v[68:69], v[0:1], 0, s[8:9]
	v_readlane_b32 s8, v254, 55
	v_lshlrev_b32_e32 v192, 3, v2
	v_readlane_b32 s9, v254, 56
	s_addc_u32 s3, s17, 0
	v_cmp_eq_u32_e64 s[6:7], 0, v2
	v_lshlrev_b32_e32 v64, 2, v2
	v_lshl_add_u64 v[70:71], s[8:9], 0, v[192:193]
	v_readlane_b32 s10, v253, 0
	v_readlane_b32 s11, v253, 63
	s_mov_b32 s101, 0
	s_cmpk_eq_u32 s11, 0x100
	s_cbranch_scc0 .LBB0_1150
	s_cmpk_lt_u32 s10, 0x6a
	s_cbranch_scc1 .LBB0_1131
	s_sub_u32 s10, s10, 0x6a
	s_lshl_b32 s10, s10, 3
	v_readfirstlane_b32 s100, v220
	s_nop 0
	s_lshr_b32 s100, s100, 6
	s_add_u32 s100, s100, s10
	s_movk_i32 s101, 0x4b0
	s_branch .LBB0_1150
